# first grid barrier: the 16 per-XCD counter loads issued together instead of 16 serial round trips
# baseline (speedup 1.0000x reference)
.LBB0_339:
	v_readlane_b32 s6, v253, 42
	v_readlane_b32 s7, v253, 43
	s_mov_b64 s[20:21], -1
	s_mov_b64 s[22:23], -1
	s_nop 2
	global_load_dword v0, v1, s[6:7] sc1
	v_readlane_b32 s6, v253, 44
	v_readlane_b32 s7, v253, 45
	s_waitcnt lgkmcnt(0)
	s_nop 3
	global_load_dword v2, v1, s[6:7] sc1
	v_readlane_b32 s6, v253, 46
	v_readlane_b32 s7, v253, 47
	s_nop 4
	global_load_dword v3, v1, s[6:7] sc1
	v_readlane_b32 s6, v253, 48
	v_readlane_b32 s7, v253, 49
	s_nop 4
	global_load_dword v4, v1, s[6:7] sc1
	v_readlane_b32 s6, v253, 50
	v_readlane_b32 s7, v253, 51
	s_nop 4
	global_load_dword v5, v1, s[6:7] sc1
	v_readlane_b32 s6, v253, 52
	v_readlane_b32 s7, v253, 53
	s_nop 4
	global_load_dword v6, v1, s[6:7] sc1
	v_readlane_b32 s6, v253, 54
	v_readlane_b32 s7, v253, 55
	s_nop 4
	global_load_dword v7, v1, s[6:7] sc1
	v_readlane_b32 s6, v253, 56
	v_readlane_b32 s7, v253, 57
	s_nop 4
	global_load_dword v8, v1, s[6:7] sc1
	v_readlane_b32 s6, v253, 58
	v_readlane_b32 s7, v253, 59
	s_nop 4
	global_load_dword v9, v1, s[6:7] sc1
	v_readlane_b32 s6, v253, 60
	v_readlane_b32 s7, v253, 61
	s_nop 4
	global_load_dword v10, v1, s[6:7] sc1
	v_readlane_b32 s6, v253, 62
	v_readlane_b32 s7, v253, 63
	s_nop 4
	global_load_dword v11, v1, s[6:7] sc1
	v_readlane_b32 s6, v254, 0
	v_readlane_b32 s7, v254, 1
	s_nop 4
	global_load_dword v12, v1, s[6:7] sc1
	v_readlane_b32 s6, v254, 2
	v_readlane_b32 s7, v254, 3
	s_nop 4
	global_load_dword v13, v1, s[6:7] sc1
	v_readlane_b32 s6, v254, 4
	v_readlane_b32 s7, v254, 5
	s_nop 4
	global_load_dword v14, v1, s[6:7] sc1
	v_readlane_b32 s6, v254, 6
	v_readlane_b32 s7, v254, 7
	s_nop 4
	global_load_dword v15, v1, s[6:7] sc1
	v_readlane_b32 s6, v254, 8
	v_readlane_b32 s7, v254, 9
	s_nop 4
	global_load_dword v16, v1, s[6:7] sc1
	s_waitcnt vmcnt(0)
	v_add_u32_e32 v17, v2, v0
	v_add_u32_e32 v17, v17, v3
	v_add_u32_e32 v17, v17, v4
	v_add_u32_e32 v17, v17, v5
	v_add_u32_e32 v17, v17, v6
	v_add_u32_e32 v17, v17, v7
	v_add_u32_e32 v17, v17, v8
	v_add_u32_e32 v17, v17, v9
	v_add_u32_e32 v17, v17, v10
	v_add_u32_e32 v17, v17, v11
	v_add_u32_e32 v17, v17, v12
	v_add_u32_e32 v17, v17, v13
	v_add_u32_e32 v17, v17, v14
	v_add_u32_e32 v17, v17, v15
	v_add_u32_e32 v17, v17, v16
	v_cmp_eq_u32_e32 vcc, s11, v17
	s_cbranch_vccnz .LBB0_338
	s_and_b32 s5, s4, 0xff
	s_cmp_eq_u32 s5, 0
	s_mov_b64 s[24:25], -1
	s_sleep 1
	s_cbranch_scc0 .LBB0_343
	v_readlane_b32 s6, v253, 40
	v_readlane_b32 s7, v253, 41
	s_nop 4
	global_load_dword v17, v1, s[6:7] sc1
	s_waitcnt vmcnt(0)
	v_cmp_eq_u32_e32 vcc, 0, v17
	s_cbranch_vccnz .LBB0_345
	s_mov_b64 s[24:25], 0
